# pa_loop_back_edge_rotated
# speedup vs baseline: 1.0021x; 1.0016x over previous
; #define PG8_STAGE(bufoff, gbase, voff) do { _Pragma("unroll") for (int _i = 0; _i < 2; ++_i) \
;         __builtin_amdgcn_global_load_lds((const unsigned*)((const char*)(gbase) + (voff)[_i]), (LAS unsigned*)(lds + (bufoff) + ldsw + _i * 8192), 16, 0, 0); } while (0)
; #define PG8_LDA(dst, b, h) do { _Pragma("unroll") for (int m = 0; m < 4; ++m) _Pragma("unroll") for (int k = 0; k < 2; ++k) dst[m][k] = *(const LAS bf16x8*)(lds + PG8_SA(b, h) + aoff + m * 2048 + k * 1024); } while (0)
; #define PG8_LDB(dst, b, h) do { _Pragma("unroll") for (int n = 0; n < 2; ++n) _Pragma("unroll") for (int k = 0; k < 2; ++k) dst[n][k] = *(const LAS bf16x8*)(lds + PG8_SB(b, h) + boff + n * 2048 + k * 1024); } while (0)
; #define PG8_MMA(ai, bj, At, Bt) do { __builtin_amdgcn_s_setprio(1); _Pragma("unroll") for (int m = 0; m < 4; ++m) _Pragma("unroll") for (int n = 0; n < 2; ++n) _Pragma("unroll") for (int k = 0; k < 2; ++k) \
;         acc[ai][bj][m][n] = __builtin_amdgcn_mfma_f32_16x16x32_bf16(Bt[n][k], At[m][k], acc[ai][bj][m][n], 0, 0, 0); __builtin_amdgcn_s_setprio(0); } while (0)
; #define PG8_WAIT_V(n) asm volatile("s_waitcnt vmcnt(" #n ")" ::: "memory")
; #define PG8_WAIT_L(n) asm volatile("s_waitcnt lgkmcnt(" #n ")" ::: "memory")
; #define PG8_BAR __builtin_amdgcn_s_barrier()
; #define PG8_SCHED __builtin_amdgcn_sched_barrier(0)
; template <class Epi, class Sched>
; __device__ __forceinline__ void gemm_phase(LAS unsigned char* lds, const Sched& S, const Epi& E, bool natural = false) {
;     ...
;             const char* a1 = cA + (size_t)(t + 1) * kstep;
;             const char* a2 = last ? nA : cA + (size_t)(t + 2) * kstep; const char* b2 = last ? nB : cB + (size_t)(t + 2) * kstep;
;             const char* a3 = a2 + kstep; const char* b3 = b2 + kstep;
;             if constexpr (Epi::MIDHOOK) { if (t == nt / 2) E.mid(acc, cur, wr, wc, fr, fq); }
;             PG8_LDB(B0, 0, 0); PG8_LDB(B1, 0, 1); PG8_SCHED; PG8_LDA(At, 0, 0); PG8_STAGE(PG8_SA(1, 1), a1 + hstep, voffA);
;             PG8_WAIT_V(8); PG8_WAIT_L(0); PG8_BAR; PG8_MMA(0, 0, At, B0); PG8_MMA(0, 1, At, B1); PG8_BAR; PG8_SCHED;
;             PG8_LDA(At, 0, 1); PG8_STAGE(PG8_SB(0, 0), b2, voffB0); PG8_STAGE(PG8_SB(0, 1), b2, voffB1); PG8_STAGE(PG8_SA(0, 0), a2, voffA);
;             PG8_WAIT_V(8); PG8_WAIT_L(0); PG8_BAR; PG8_MMA(1, 0, At, B0); PG8_MMA(1, 1, At, B1); PG8_BAR; PG8_SCHED;
.LBB0_173:
	s_add_u32 s40, s40, 0x40080
	s_addc_u32 s41, s41, 0
	s_add_u32 s31, s42, 0x100
	s_addc_u32 s35, s43, 0
	s_mov_b32 s71, -2
	ds_read_b128 v[128:131], v196
	ds_read_b128 v[132:135], v196 offset:1024
	ds_read_b128 v[136:139], v196 offset:2048
	ds_read_b128 v[140:143], v196 offset:3072
	ds_read_b128 v[144:147], v197
	ds_read_b128 v[148:151], v197 offset:1024
	ds_read_b128 v[186:189], v197 offset:2048
	ds_read_b128 v[202:205], v197 offset:3072
	s_add_u32 s42, s40, 0xfffc0080
	s_addc_u32 s43, s41, -1
	s_cmp_eq_u32 s71, 12
	s_cselect_b32 s45, s1, s43
	s_cselect_b32 s44, s0, s42
	s_cselect_b32 s43, s37, s35
	s_cselect_b32 s42, s36, s31
	v_lshl_add_u64 v[238:239], s[40:41], 0, v[178:179]
	s_add_i32 m0, s39, 0xc000
	ds_read_b128 v[206:209], v198
	ds_read_b128 v[210:213], v198 offset:1024
	ds_read_b128 v[214:217], v198 offset:2048
	ds_read_b128 v[218:221], v198 offset:3072
	ds_read_b128 v[222:225], v198 offset:4096
	ds_read_b128 v[226:229], v198 offset:5120
	ds_read_b128 v[230:233], v198 offset:6144
	ds_read_b128 v[234:237], v198 offset:7168
	global_load_lds_dwordx4 v[238:239], off
	v_lshl_add_u64 v[238:239], s[40:41], 0, v[180:181]
	s_add_i32 m0, s39, 0xe000
	s_nop 0
	global_load_lds_dwordx4 v[238:239], off
	s_waitcnt vmcnt(8)
	s_waitcnt lgkmcnt(0)
	s_barrier
	s_setprio 1
	s_waitcnt lgkmcnt(0)
	v_mfma_f32_16x16x32_bf16 v[124:127], v[128:131], v[206:209], 0
	v_mfma_f32_16x16x32_bf16 v[120:123], v[136:139], v[206:209], 0
	v_mfma_f32_16x16x32_bf16 v[108:111], v[128:131], v[214:217], 0
	v_mfma_f32_16x16x32_bf16 v[104:107], v[136:139], v[214:217], 0
	v_mfma_f32_16x16x32_bf16 v[92:95], v[128:131], v[222:225], 0
	v_mfma_f32_16x16x32_bf16 v[88:91], v[136:139], v[222:225], 0
	v_mfma_f32_16x16x32_bf16 v[76:79], v[128:131], v[230:233], 0
	v_mfma_f32_16x16x32_bf16 v[72:75], v[136:139], v[230:233], 0
	v_mfma_f32_16x16x32_bf16 v[124:127], v[132:135], v[210:213], v[124:127]
	v_mfma_f32_16x16x32_bf16 v[120:123], v[140:143], v[210:213], v[120:123]
	v_mfma_f32_16x16x32_bf16 v[108:111], v[132:135], v[218:221], v[108:111]
	v_mfma_f32_16x16x32_bf16 v[104:107], v[140:143], v[218:221], v[104:107]
	v_mfma_f32_16x16x32_bf16 v[92:95], v[132:135], v[226:229], v[92:95]
	v_mfma_f32_16x16x32_bf16 v[88:91], v[140:143], v[226:229], v[88:91]
	v_mfma_f32_16x16x32_bf16 v[76:79], v[132:135], v[234:237], v[76:79]
	v_mfma_f32_16x16x32_bf16 v[72:75], v[140:143], v[234:237], v[72:75]
	s_setprio 0
	s_setprio 1
	v_mfma_f32_16x16x32_bf16 v[116:119], v[144:147], v[206:209], 0
	v_mfma_f32_16x16x32_bf16 v[112:115], v[186:189], v[206:209], 0
	v_mfma_f32_16x16x32_bf16 v[100:103], v[144:147], v[214:217], 0
	v_mfma_f32_16x16x32_bf16 v[96:99], v[186:189], v[214:217], 0
	v_mfma_f32_16x16x32_bf16 v[84:87], v[144:147], v[222:225], 0
	v_mfma_f32_16x16x32_bf16 v[80:83], v[186:189], v[222:225], 0
	v_mfma_f32_16x16x32_bf16 v[68:71], v[144:147], v[230:233], 0
	v_mfma_f32_16x16x32_bf16 v[64:67], v[186:189], v[230:233], 0
	v_mfma_f32_16x16x32_bf16 v[116:119], v[148:151], v[210:213], v[116:119]
	v_mfma_f32_16x16x32_bf16 v[112:115], v[202:205], v[210:213], v[112:115]
	v_mfma_f32_16x16x32_bf16 v[100:103], v[148:151], v[218:221], v[100:103]
	v_mfma_f32_16x16x32_bf16 v[96:99], v[202:205], v[218:221], v[96:99]
	v_mfma_f32_16x16x32_bf16 v[84:87], v[148:151], v[226:229], v[84:87]
	v_mfma_f32_16x16x32_bf16 v[80:83], v[202:205], v[226:229], v[80:83]
	v_mfma_f32_16x16x32_bf16 v[68:71], v[148:151], v[234:237], v[68:71]
	v_mfma_f32_16x16x32_bf16 v[64:67], v[202:205], v[234:237], v[64:67]
	s_setprio 0
	s_barrier
	s_add_i32 s72, s59, s33
	v_lshl_add_u64 v[238:239], s[42:43], 0, v[156:157]
	s_mov_b32 m0, s72
	ds_read_b128 v[206:209], v198 offset:16384
	ds_read_b128 v[210:213], v198 offset:17408
	ds_read_b128 v[214:217], v198 offset:18432
	ds_read_b128 v[218:221], v198 offset:19456
	ds_read_b128 v[222:225], v198 offset:20480
	ds_read_b128 v[226:229], v198 offset:21504
	ds_read_b128 v[230:233], v198 offset:22528
	ds_read_b128 v[234:237], v198 offset:23552
	global_load_lds_dwordx4 v[238:239], off
	v_lshl_add_u64 v[240:241], s[42:43], 0, v[162:163]
	s_add_i32 m0, s72, 0x2000
	s_add_i32 s72, s60, s33
	global_load_lds_dwordx4 v[240:241], off
	v_lshl_add_u64 v[242:243], s[42:43], 0, v[158:159]
	s_mov_b32 m0, s72
	v_lshl_add_u64 v[244:245], s[44:45], 0, v[160:161]
	global_load_lds_dwordx4 v[242:243], off
	v_lshl_add_u64 v[242:243], s[42:43], 0, v[164:165]
	s_add_i32 m0, s72, 0x2000
	s_nop 0
	global_load_lds_dwordx4 v[242:243], off
	v_lshl_add_u64 v[242:243], s[44:45], 0, v[154:155]
	s_mov_b32 m0, s39
	s_nop 0
	global_load_lds_dwordx4 v[242:243], off
	s_mov_b32 m0, s46
	s_nop 0
	global_load_lds_dwordx4 v[244:245], off
	s_waitcnt vmcnt(8)
	s_waitcnt lgkmcnt(0)
	s_barrier
; #define PG8_STAGE(bufoff, gbase, voff) do { _Pragma("unroll") for (int _i = 0; _i < 2; ++_i) \
;         __builtin_amdgcn_global_load_lds((const unsigned*)((const char*)(gbase) + (voff)[_i]), (LAS unsigned*)(lds + (bufoff) + ldsw + _i * 8192), 16, 0, 0); } while (0)
; #define PG8_LDA(dst, b, h) do { _Pragma("unroll") for (int m = 0; m < 4; ++m) _Pragma("unroll") for (int k = 0; k < 2; ++k) dst[m][k] = *(const LAS bf16x8*)(lds + PG8_SA(b, h) + aoff + m * 2048 + k * 1024); } while (0)
; #define PG8_LDB(dst, b, h) do { _Pragma("unroll") for (int n = 0; n < 2; ++n) _Pragma("unroll") for (int k = 0; k < 2; ++k) dst[n][k] = *(const LAS bf16x8*)(lds + PG8_SB(b, h) + boff + n * 2048 + k * 1024); } while (0)
; #define PG8_MMA(ai, bj, At, Bt) do { __builtin_amdgcn_s_setprio(1); _Pragma("unroll") for (int m = 0; m < 4; ++m) _Pragma("unroll") for (int n = 0; n < 2; ++n) _Pragma("unroll") for (int k = 0; k < 2; ++k) \
;         acc[ai][bj][m][n] = __builtin_amdgcn_mfma_f32_16x16x32_bf16(Bt[n][k], At[m][k], acc[ai][bj][m][n], 0, 0, 0); __builtin_amdgcn_s_setprio(0); } while (0)
; #define PG8_WAIT_V(n) asm volatile("s_waitcnt vmcnt(" #n ")" ::: "memory")
; #define PG8_WAIT_L(n) asm volatile("s_waitcnt lgkmcnt(" #n ")" ::: "memory")
; #define PG8_BAR __builtin_amdgcn_s_barrier()
; #define PG8_SCHED __builtin_amdgcn_sched_barrier(0)
; template <class Epi, class Sched>
; __device__ __forceinline__ void gemm_phase(LAS unsigned char* lds, const Sched& S, const Epi& E, bool natural = false) {
;     ...
;             PG8_WAIT_V(8); PG8_WAIT_L(0); PG8_BAR; PG8_MMA(1, 0, At, B0); PG8_MMA(1, 1, At, B1); PG8_BAR; PG8_SCHED;
;             PG8_LDB(B0, 1, 0); PG8_LDB(B1, 1, 1); PG8_SCHED; PG8_LDA(At, 1, 0); PG8_STAGE(PG8_SA(0, 1), a2 + hstep, voffA);
;             PG8_WAIT_V(8); PG8_WAIT_L(0); PG8_BAR; PG8_MMA(0, 0, At, B0); PG8_MMA(0, 1, At, B1); PG8_BAR; PG8_SCHED;
	s_setprio 1
	s_waitcnt lgkmcnt(0)
	v_mfma_f32_16x16x32_bf16 v[60:63], v[128:131], v[206:209], 0
	v_mfma_f32_16x16x32_bf16 v[56:59], v[136:139], v[206:209], 0
	v_mfma_f32_16x16x32_bf16 v[44:47], v[128:131], v[214:217], 0
	v_mfma_f32_16x16x32_bf16 v[40:43], v[136:139], v[214:217], 0
	v_mfma_f32_16x16x32_bf16 v[28:31], v[128:131], v[222:225], 0
	v_mfma_f32_16x16x32_bf16 v[24:27], v[136:139], v[222:225], 0
	v_mfma_f32_16x16x32_bf16 v[12:15], v[128:131], v[230:233], 0
	v_mfma_f32_16x16x32_bf16 v[8:11], v[136:139], v[230:233], 0
	v_mfma_f32_16x16x32_bf16 v[60:63], v[132:135], v[210:213], v[60:63]
	v_mfma_f32_16x16x32_bf16 v[56:59], v[140:143], v[210:213], v[56:59]
	v_mfma_f32_16x16x32_bf16 v[44:47], v[132:135], v[218:221], v[44:47]
	v_mfma_f32_16x16x32_bf16 v[40:43], v[140:143], v[218:221], v[40:43]
	v_mfma_f32_16x16x32_bf16 v[28:31], v[132:135], v[226:229], v[28:31]
	v_mfma_f32_16x16x32_bf16 v[24:27], v[140:143], v[226:229], v[24:27]
	v_mfma_f32_16x16x32_bf16 v[12:15], v[132:135], v[234:237], v[12:15]
	v_mfma_f32_16x16x32_bf16 v[8:11], v[140:143], v[234:237], v[8:11]
	s_setprio 0
	s_setprio 1
	v_mfma_f32_16x16x32_bf16 v[52:55], v[144:147], v[206:209], 0
	v_mfma_f32_16x16x32_bf16 v[48:51], v[186:189], v[206:209], 0
	v_mfma_f32_16x16x32_bf16 v[36:39], v[144:147], v[214:217], 0
	v_mfma_f32_16x16x32_bf16 v[32:35], v[186:189], v[214:217], 0
	v_mfma_f32_16x16x32_bf16 v[20:23], v[144:147], v[222:225], 0
	v_mfma_f32_16x16x32_bf16 v[16:19], v[186:189], v[222:225], 0
	v_mfma_f32_16x16x32_bf16 v[4:7], v[144:147], v[230:233], 0
	v_mfma_f32_16x16x32_bf16 v[0:3], v[186:189], v[230:233], 0
	v_mfma_f32_16x16x32_bf16 v[52:55], v[148:151], v[210:213], v[52:55]
	v_mfma_f32_16x16x32_bf16 v[48:51], v[202:205], v[210:213], v[48:51]
	v_mfma_f32_16x16x32_bf16 v[36:39], v[148:151], v[218:221], v[36:39]
	v_mfma_f32_16x16x32_bf16 v[32:35], v[202:205], v[218:221], v[32:35]
	v_mfma_f32_16x16x32_bf16 v[20:23], v[148:151], v[226:229], v[20:23]
	v_mfma_f32_16x16x32_bf16 v[16:19], v[202:205], v[226:229], v[16:19]
	v_mfma_f32_16x16x32_bf16 v[4:7], v[148:151], v[234:237], v[4:7]
	v_mfma_f32_16x16x32_bf16 v[0:3], v[202:205], v[234:237], v[0:3]
	s_setprio 0
	s_barrier
	s_add_i32 s72, 0, 0x18000
	s_add_i32 s73, 0, 0x1c000
	v_add_u32_e32 v140, s72, v192
	v_add_u32_e32 v166, s73, v192
	ds_read_b128 v[128:131], v140
	ds_read_b128 v[132:135], v140 offset:1024
	ds_read_b128 v[136:139], v140 offset:2048
	ds_read_b128 v[140:143], v140 offset:3072
	ds_read_b128 v[144:147], v166
	ds_read_b128 v[148:151], v166 offset:1024
	ds_read_b128 v[186:189], v166 offset:2048
	ds_read_b128 v[202:205], v166 offset:3072
	s_add_u32 s44, s44, 0x40000
	s_addc_u32 s45, s45, 0
	s_mov_b32 m0, s47
	v_lshl_add_u64 v[246:247], s[44:45], 0, v[154:155]
	ds_read_b128 v[206:209], v198 offset:32768
	ds_read_b128 v[210:213], v198 offset:33792
	ds_read_b128 v[214:217], v198 offset:34816
	ds_read_b128 v[218:221], v198 offset:35840
	ds_read_b128 v[222:225], v198 offset:36864
	ds_read_b128 v[226:229], v198 offset:37888
	ds_read_b128 v[230:233], v198 offset:38912
	ds_read_b128 v[234:237], v198 offset:39936
	global_load_lds_dwordx4 v[246:247], off
	v_lshl_add_u64 v[246:247], s[44:45], 0, v[160:161]
	s_mov_b32 m0, s49
	s_nop 0
	global_load_lds_dwordx4 v[246:247], off
	s_waitcnt vmcnt(8)
	s_waitcnt lgkmcnt(0)
	s_barrier
	s_setprio 1
	s_waitcnt lgkmcnt(0)
	v_mfma_f32_16x16x32_bf16 v[124:127], v[128:131], v[206:209], v[124:127]
	v_mfma_f32_16x16x32_bf16 v[120:123], v[136:139], v[206:209], v[120:123]
	v_mfma_f32_16x16x32_bf16 v[108:111], v[128:131], v[214:217], v[108:111]
	v_mfma_f32_16x16x32_bf16 v[104:107], v[136:139], v[214:217], v[104:107]
	v_mfma_f32_16x16x32_bf16 v[92:95], v[128:131], v[222:225], v[92:95]
	v_mfma_f32_16x16x32_bf16 v[88:91], v[136:139], v[222:225], v[88:91]
	v_mfma_f32_16x16x32_bf16 v[76:79], v[128:131], v[230:233], v[76:79]
	v_mfma_f32_16x16x32_bf16 v[72:75], v[136:139], v[230:233], v[72:75]
	v_mfma_f32_16x16x32_bf16 v[124:127], v[132:135], v[210:213], v[124:127]
	v_mfma_f32_16x16x32_bf16 v[120:123], v[140:143], v[210:213], v[120:123]
	v_mfma_f32_16x16x32_bf16 v[108:111], v[132:135], v[218:221], v[108:111]
	v_mfma_f32_16x16x32_bf16 v[104:107], v[140:143], v[218:221], v[104:107]
	v_mfma_f32_16x16x32_bf16 v[92:95], v[132:135], v[226:229], v[92:95]
	v_mfma_f32_16x16x32_bf16 v[88:91], v[140:143], v[226:229], v[88:91]
	v_mfma_f32_16x16x32_bf16 v[76:79], v[132:135], v[234:237], v[76:79]
	v_mfma_f32_16x16x32_bf16 v[72:75], v[140:143], v[234:237], v[72:75]
	s_setprio 0
	s_setprio 1
	v_mfma_f32_16x16x32_bf16 v[116:119], v[144:147], v[206:209], v[116:119]
	v_mfma_f32_16x16x32_bf16 v[112:115], v[186:189], v[206:209], v[112:115]
	v_mfma_f32_16x16x32_bf16 v[100:103], v[144:147], v[214:217], v[100:103]
	v_mfma_f32_16x16x32_bf16 v[96:99], v[186:189], v[214:217], v[96:99]
	v_mfma_f32_16x16x32_bf16 v[84:87], v[144:147], v[222:225], v[84:87]
	v_mfma_f32_16x16x32_bf16 v[80:83], v[186:189], v[222:225], v[80:83]
	v_mfma_f32_16x16x32_bf16 v[68:71], v[144:147], v[230:233], v[68:71]
	v_mfma_f32_16x16x32_bf16 v[64:67], v[186:189], v[230:233], v[64:67]
	v_mfma_f32_16x16x32_bf16 v[116:119], v[148:151], v[210:213], v[116:119]
	v_mfma_f32_16x16x32_bf16 v[112:115], v[202:205], v[210:213], v[112:115]
	v_mfma_f32_16x16x32_bf16 v[100:103], v[148:151], v[218:221], v[100:103]
	v_mfma_f32_16x16x32_bf16 v[96:99], v[202:205], v[218:221], v[96:99]
	v_mfma_f32_16x16x32_bf16 v[84:87], v[148:151], v[226:229], v[84:87]
	v_mfma_f32_16x16x32_bf16 v[80:83], v[202:205], v[226:229], v[80:83]
	v_mfma_f32_16x16x32_bf16 v[68:71], v[148:151], v[234:237], v[68:71]
	v_mfma_f32_16x16x32_bf16 v[64:67], v[202:205], v[234:237], v[64:67]
	s_setprio 0
	s_barrier
; #define PG8_STAGE(bufoff, gbase, voff) do { _Pragma("unroll") for (int _i = 0; _i < 2; ++_i) \
;         __builtin_amdgcn_global_load_lds((const unsigned*)((const char*)(gbase) + (voff)[_i]), (LAS unsigned*)(lds + (bufoff) + ldsw + _i * 8192), 16, 0, 0); } while (0)
; #define PG8_LDA(dst, b, h) do { _Pragma("unroll") for (int m = 0; m < 4; ++m) _Pragma("unroll") for (int k = 0; k < 2; ++k) dst[m][k] = *(const LAS bf16x8*)(lds + PG8_SA(b, h) + aoff + m * 2048 + k * 1024); } while (0)
; #define PG8_LDB(dst, b, h) do { _Pragma("unroll") for (int n = 0; n < 2; ++n) _Pragma("unroll") for (int k = 0; k < 2; ++k) dst[n][k] = *(const LAS bf16x8*)(lds + PG8_SB(b, h) + boff + n * 2048 + k * 1024); } while (0)
; #define PG8_MMA(ai, bj, At, Bt) do { __builtin_amdgcn_s_setprio(1); _Pragma("unroll") for (int m = 0; m < 4; ++m) _Pragma("unroll") for (int n = 0; n < 2; ++n) _Pragma("unroll") for (int k = 0; k < 2; ++k) \
;         acc[ai][bj][m][n] = __builtin_amdgcn_mfma_f32_16x16x32_bf16(Bt[n][k], At[m][k], acc[ai][bj][m][n], 0, 0, 0); __builtin_amdgcn_s_setprio(0); } while (0)
; #define PG8_WAIT_V(n) asm volatile("s_waitcnt vmcnt(" #n ")" ::: "memory")
; #define PG8_WAIT_L(n) asm volatile("s_waitcnt lgkmcnt(" #n ")" ::: "memory")
; #define PG8_BAR __builtin_amdgcn_s_barrier()
; #define PG8_SCHED __builtin_amdgcn_sched_barrier(0)
; template <class Epi, class Sched>
; __device__ __forceinline__ void gemm_phase(LAS unsigned char* lds, const Sched& S, const Epi& E, bool natural = false) {
;     ...
;             PG8_LDB(B0, 0, 0); PG8_LDB(B1, 0, 1); PG8_SCHED; PG8_LDA(At, 0, 0); PG8_STAGE(PG8_SA(1, 1), a1 + hstep, voffA);
;             PG8_WAIT_V(8); PG8_WAIT_L(0); PG8_BAR; PG8_MMA(0, 0, At, B0); PG8_MMA(0, 1, At, B1); PG8_BAR; PG8_SCHED;
;     ...
;             PG8_LDA(At, 1, 1); PG8_STAGE(PG8_SB(1, 0), b3, voffB0); PG8_STAGE(PG8_SB(1, 1), b3, voffB1); PG8_STAGE(PG8_SA(1, 0), a3, voffA);
;             PG8_WAIT_V(8); PG8_WAIT_L(0); PG8_BAR; PG8_MMA(1, 0, At, B0); PG8_MMA(1, 1, At, B1); PG8_BAR; PG8_SCHED;
;         }
	s_add_u32 s42, s42, 0x80
	s_addc_u32 s43, s43, 0
	s_add_i32 s44, s72, s33
	v_lshl_add_u64 v[238:239], v[238:239], 0, s[12:13]
	s_mov_b32 m0, s44
	ds_read_b128 v[206:209], v198 offset:49152
	ds_read_b128 v[210:213], v198 offset:50176
	ds_read_b128 v[214:217], v198 offset:51200
	ds_read_b128 v[218:221], v198 offset:52224
	ds_read_b128 v[222:225], v198 offset:53248
	ds_read_b128 v[226:229], v198 offset:54272
	ds_read_b128 v[230:233], v198 offset:55296
	ds_read_b128 v[234:237], v198 offset:56320
	global_load_lds_dwordx4 v[238:239], off
	v_lshl_add_u64 v[238:239], v[240:241], 0, s[12:13]
	s_add_i32 m0, s44, 0x2000
	s_add_i32 s44, s73, s33
	global_load_lds_dwordx4 v[238:239], off
	v_lshl_add_u64 v[238:239], s[42:43], 0, v[158:159]
	s_mov_b32 m0, s44
	s_nop 0
	global_load_lds_dwordx4 v[238:239], off
	v_lshl_add_u64 v[238:239], s[42:43], 0, v[164:165]
	s_add_i32 m0, s44, 0x2000
	s_nop 0
	global_load_lds_dwordx4 v[238:239], off
	v_lshl_add_u64 v[238:239], v[242:243], 0, s[12:13]
	s_mov_b32 m0, s51
	s_nop 0
	global_load_lds_dwordx4 v[238:239], off
	v_lshl_add_u64 v[238:239], v[244:245], 0, s[12:13]
	s_mov_b32 m0, s52
	s_nop 0
	global_load_lds_dwordx4 v[238:239], off
	s_waitcnt vmcnt(8)
	s_waitcnt lgkmcnt(0)
	s_barrier
	s_setprio 1
	s_waitcnt lgkmcnt(0)
	v_mfma_f32_16x16x32_bf16 v[60:63], v[128:131], v[206:209], v[60:63]
	v_mfma_f32_16x16x32_bf16 v[56:59], v[136:139], v[206:209], v[56:59]
	v_mfma_f32_16x16x32_bf16 v[44:47], v[128:131], v[214:217], v[44:47]
	v_mfma_f32_16x16x32_bf16 v[40:43], v[136:139], v[214:217], v[40:43]
	v_mfma_f32_16x16x32_bf16 v[28:31], v[128:131], v[222:225], v[28:31]
	v_mfma_f32_16x16x32_bf16 v[24:27], v[136:139], v[222:225], v[24:27]
	v_mfma_f32_16x16x32_bf16 v[12:15], v[128:131], v[230:233], v[12:15]
	v_mfma_f32_16x16x32_bf16 v[8:11], v[136:139], v[230:233], v[8:11]
	v_mfma_f32_16x16x32_bf16 v[60:63], v[132:135], v[210:213], v[60:63]
	v_mfma_f32_16x16x32_bf16 v[56:59], v[140:143], v[210:213], v[56:59]
	v_mfma_f32_16x16x32_bf16 v[44:47], v[132:135], v[218:221], v[44:47]
	v_mfma_f32_16x16x32_bf16 v[40:43], v[140:143], v[218:221], v[40:43]
	v_mfma_f32_16x16x32_bf16 v[28:31], v[132:135], v[226:229], v[28:31]
	v_mfma_f32_16x16x32_bf16 v[24:27], v[140:143], v[226:229], v[24:27]
	v_mfma_f32_16x16x32_bf16 v[12:15], v[132:135], v[234:237], v[12:15]
	v_mfma_f32_16x16x32_bf16 v[8:11], v[140:143], v[234:237], v[8:11]
	s_setprio 0
	s_setprio 1
	v_mfma_f32_16x16x32_bf16 v[52:55], v[144:147], v[206:209], v[52:55]
	v_mfma_f32_16x16x32_bf16 v[48:51], v[186:189], v[206:209], v[48:51]
	v_mfma_f32_16x16x32_bf16 v[36:39], v[144:147], v[214:217], v[36:39]
	v_mfma_f32_16x16x32_bf16 v[32:35], v[186:189], v[214:217], v[32:35]
	v_mfma_f32_16x16x32_bf16 v[20:23], v[144:147], v[222:225], v[20:23]
	v_mfma_f32_16x16x32_bf16 v[16:19], v[186:189], v[222:225], v[16:19]
	v_mfma_f32_16x16x32_bf16 v[4:7], v[144:147], v[230:233], v[4:7]
	v_mfma_f32_16x16x32_bf16 v[0:3], v[186:189], v[230:233], v[0:3]
	v_mfma_f32_16x16x32_bf16 v[52:55], v[148:151], v[210:213], v[52:55]
	v_mfma_f32_16x16x32_bf16 v[48:51], v[202:205], v[210:213], v[48:51]
	v_mfma_f32_16x16x32_bf16 v[36:39], v[148:151], v[218:221], v[36:39]
	v_mfma_f32_16x16x32_bf16 v[32:35], v[202:205], v[218:221], v[32:35]
	v_mfma_f32_16x16x32_bf16 v[20:23], v[148:151], v[226:229], v[20:23]
	v_mfma_f32_16x16x32_bf16 v[16:19], v[202:205], v[226:229], v[16:19]
	v_mfma_f32_16x16x32_bf16 v[4:7], v[148:151], v[234:237], v[4:7]
	v_mfma_f32_16x16x32_bf16 v[0:3], v[202:205], v[234:237], v[0:3]
	s_add_i32 s71, s71, 2
	s_add_u32 s40, s40, 0x100
	s_addc_u32 s41, s41, 0
	s_add_u32 s31, s31, 0x100
	s_addc_u32 s35, s35, 0
	s_cmp_gt_u32 s71, 13
	s_setprio 0
	s_barrier
	s_cbranch_scc0 .LBB0_174
.LBB0_174:
	ds_read_b128 v[128:131], v196
	ds_read_b128 v[132:135], v196 offset:1024
	ds_read_b128 v[136:139], v196 offset:2048
	ds_read_b128 v[140:143], v196 offset:3072
	ds_read_b128 v[144:147], v197
	ds_read_b128 v[148:151], v197 offset:1024
	ds_read_b128 v[186:189], v197 offset:2048
	ds_read_b128 v[202:205], v197 offset:3072
	s_add_u32 s42, s40, 0xfffc0080
	s_addc_u32 s43, s41, -1
	s_cmp_eq_u32 s71, 12
	s_cselect_b32 s45, s1, s43
	s_cselect_b32 s44, s0, s42
	s_cselect_b32 s43, s37, s35
	s_cselect_b32 s42, s36, s31
	v_lshl_add_u64 v[238:239], s[40:41], 0, v[178:179]
	s_add_i32 m0, s39, 0xc000
	ds_read_b128 v[206:209], v198
	ds_read_b128 v[210:213], v198 offset:1024
	ds_read_b128 v[214:217], v198 offset:2048
	ds_read_b128 v[218:221], v198 offset:3072
	ds_read_b128 v[222:225], v198 offset:4096
	ds_read_b128 v[226:229], v198 offset:5120
	ds_read_b128 v[230:233], v198 offset:6144
	ds_read_b128 v[234:237], v198 offset:7168
	global_load_lds_dwordx4 v[238:239], off
	v_lshl_add_u64 v[238:239], s[40:41], 0, v[180:181]
	s_add_i32 m0, s39, 0xe000
	s_nop 0
	global_load_lds_dwordx4 v[238:239], off
	s_waitcnt vmcnt(8)
	s_waitcnt lgkmcnt(0)
	s_barrier
; #define PG8_STAGE(bufoff, gbase, voff) do { _Pragma("unroll") for (int _i = 0; _i < 2; ++_i) \
;         __builtin_amdgcn_global_load_lds((const unsigned*)((const char*)(gbase) + (voff)[_i]), (LAS unsigned*)(lds + (bufoff) + ldsw + _i * 8192), 16, 0, 0); } while (0)
; #define PG8_LDA(dst, b, h) do { _Pragma("unroll") for (int m = 0; m < 4; ++m) _Pragma("unroll") for (int k = 0; k < 2; ++k) dst[m][k] = *(const LAS bf16x8*)(lds + PG8_SA(b, h) + aoff + m * 2048 + k * 1024); } while (0)
; #define PG8_MMA(ai, bj, At, Bt) do { __builtin_amdgcn_s_setprio(1); _Pragma("unroll") for (int m = 0; m < 4; ++m) _Pragma("unroll") for (int n = 0; n < 2; ++n) _Pragma("unroll") for (int k = 0; k < 2; ++k) \
;         acc[ai][bj][m][n] = __builtin_amdgcn_mfma_f32_16x16x32_bf16(Bt[n][k], At[m][k], acc[ai][bj][m][n], 0, 0, 0); __builtin_amdgcn_s_setprio(0); } while (0)
; #define PG8_WAIT_V(n) asm volatile("s_waitcnt vmcnt(" #n ")" ::: "memory")
; #define PG8_WAIT_L(n) asm volatile("s_waitcnt lgkmcnt(" #n ")" ::: "memory")
; #define PG8_BAR __builtin_amdgcn_s_barrier()
; #define PG8_SCHED __builtin_amdgcn_sched_barrier(0)
; template <class Epi, class Sched>
; __device__ __forceinline__ void gemm_phase(LAS unsigned char* lds, const Sched& S, const Epi& E, bool natural = false) {
;     ...
;             PG8_WAIT_V(8); PG8_WAIT_L(0); PG8_BAR; PG8_MMA(0, 0, At, B0); PG8_MMA(0, 1, At, B1); PG8_BAR; PG8_SCHED;
;             PG8_LDA(At, 0, 1); PG8_STAGE(PG8_SB(0, 0), b2, voffB0); PG8_STAGE(PG8_SB(0, 1), b2, voffB1); PG8_STAGE(PG8_SA(0, 0), a2, voffA);
;             PG8_WAIT_V(8); PG8_WAIT_L(0); PG8_BAR; PG8_MMA(1, 0, At, B0); PG8_MMA(1, 1, At, B1); PG8_BAR; PG8_SCHED;
	s_setprio 1
	s_waitcnt lgkmcnt(0)
	v_mfma_f32_16x16x32_bf16 v[124:127], v[128:131], v[206:209], v[124:127]
	v_mfma_f32_16x16x32_bf16 v[120:123], v[136:139], v[206:209], v[120:123]
	v_mfma_f32_16x16x32_bf16 v[108:111], v[128:131], v[214:217], v[108:111]
	v_mfma_f32_16x16x32_bf16 v[104:107], v[136:139], v[214:217], v[104:107]
	v_mfma_f32_16x16x32_bf16 v[92:95], v[128:131], v[222:225], v[92:95]
	v_mfma_f32_16x16x32_bf16 v[88:91], v[136:139], v[222:225], v[88:91]
	v_mfma_f32_16x16x32_bf16 v[76:79], v[128:131], v[230:233], v[76:79]
	v_mfma_f32_16x16x32_bf16 v[72:75], v[136:139], v[230:233], v[72:75]
	v_mfma_f32_16x16x32_bf16 v[124:127], v[132:135], v[210:213], v[124:127]
	v_mfma_f32_16x16x32_bf16 v[120:123], v[140:143], v[210:213], v[120:123]
	v_mfma_f32_16x16x32_bf16 v[108:111], v[132:135], v[218:221], v[108:111]
	v_mfma_f32_16x16x32_bf16 v[104:107], v[140:143], v[218:221], v[104:107]
	v_mfma_f32_16x16x32_bf16 v[92:95], v[132:135], v[226:229], v[92:95]
	v_mfma_f32_16x16x32_bf16 v[88:91], v[140:143], v[226:229], v[88:91]
	v_mfma_f32_16x16x32_bf16 v[76:79], v[132:135], v[234:237], v[76:79]
	v_mfma_f32_16x16x32_bf16 v[72:75], v[140:143], v[234:237], v[72:75]
	s_setprio 0
	s_setprio 1
	v_mfma_f32_16x16x32_bf16 v[116:119], v[144:147], v[206:209], v[116:119]
	v_mfma_f32_16x16x32_bf16 v[112:115], v[186:189], v[206:209], v[112:115]
	v_mfma_f32_16x16x32_bf16 v[100:103], v[144:147], v[214:217], v[100:103]
	v_mfma_f32_16x16x32_bf16 v[96:99], v[186:189], v[214:217], v[96:99]
	v_mfma_f32_16x16x32_bf16 v[84:87], v[144:147], v[222:225], v[84:87]
	v_mfma_f32_16x16x32_bf16 v[80:83], v[186:189], v[222:225], v[80:83]
	v_mfma_f32_16x16x32_bf16 v[68:71], v[144:147], v[230:233], v[68:71]
	v_mfma_f32_16x16x32_bf16 v[64:67], v[186:189], v[230:233], v[64:67]
	v_mfma_f32_16x16x32_bf16 v[116:119], v[148:151], v[210:213], v[116:119]
	v_mfma_f32_16x16x32_bf16 v[112:115], v[202:205], v[210:213], v[112:115]
	v_mfma_f32_16x16x32_bf16 v[100:103], v[148:151], v[218:221], v[100:103]
	v_mfma_f32_16x16x32_bf16 v[96:99], v[202:205], v[218:221], v[96:99]
	v_mfma_f32_16x16x32_bf16 v[84:87], v[148:151], v[226:229], v[84:87]
	v_mfma_f32_16x16x32_bf16 v[80:83], v[202:205], v[226:229], v[80:83]
	v_mfma_f32_16x16x32_bf16 v[68:71], v[148:151], v[234:237], v[68:71]
	v_mfma_f32_16x16x32_bf16 v[64:67], v[202:205], v[234:237], v[64:67]
	s_setprio 0
	s_barrier
	s_add_i32 s72, s59, s33
	v_lshl_add_u64 v[238:239], s[42:43], 0, v[156:157]
	s_mov_b32 m0, s72
	ds_read_b128 v[206:209], v198 offset:16384
	ds_read_b128 v[210:213], v198 offset:17408
	ds_read_b128 v[214:217], v198 offset:18432
	ds_read_b128 v[218:221], v198 offset:19456
	ds_read_b128 v[222:225], v198 offset:20480
	ds_read_b128 v[226:229], v198 offset:21504
	ds_read_b128 v[230:233], v198 offset:22528
	ds_read_b128 v[234:237], v198 offset:23552
	global_load_lds_dwordx4 v[238:239], off
	v_lshl_add_u64 v[240:241], s[42:43], 0, v[162:163]
	s_add_i32 m0, s72, 0x2000
	s_add_i32 s72, s60, s33
	global_load_lds_dwordx4 v[240:241], off
	v_lshl_add_u64 v[242:243], s[42:43], 0, v[158:159]
	s_mov_b32 m0, s72
	v_lshl_add_u64 v[244:245], s[44:45], 0, v[160:161]
	global_load_lds_dwordx4 v[242:243], off
	v_lshl_add_u64 v[242:243], s[42:43], 0, v[164:165]
	s_add_i32 m0, s72, 0x2000
	s_nop 0
	global_load_lds_dwordx4 v[242:243], off
	v_lshl_add_u64 v[242:243], s[44:45], 0, v[154:155]
	s_mov_b32 m0, s39
	s_nop 0
	global_load_lds_dwordx4 v[242:243], off
	s_mov_b32 m0, s46
	s_nop 0
	global_load_lds_dwordx4 v[244:245], off
	s_waitcnt vmcnt(8)
	s_waitcnt lgkmcnt(0)
	s_barrier
	s_setprio 1
	s_waitcnt lgkmcnt(0)
	v_mfma_f32_16x16x32_bf16 v[60:63], v[128:131], v[206:209], v[60:63]
	v_mfma_f32_16x16x32_bf16 v[56:59], v[136:139], v[206:209], v[56:59]
	v_mfma_f32_16x16x32_bf16 v[44:47], v[128:131], v[214:217], v[44:47]
	v_mfma_f32_16x16x32_bf16 v[40:43], v[136:139], v[214:217], v[40:43]
	v_mfma_f32_16x16x32_bf16 v[28:31], v[128:131], v[222:225], v[28:31]
	v_mfma_f32_16x16x32_bf16 v[24:27], v[136:139], v[222:225], v[24:27]
	v_mfma_f32_16x16x32_bf16 v[12:15], v[128:131], v[230:233], v[12:15]
	v_mfma_f32_16x16x32_bf16 v[8:11], v[136:139], v[230:233], v[8:11]
	v_mfma_f32_16x16x32_bf16 v[60:63], v[132:135], v[210:213], v[60:63]
	v_mfma_f32_16x16x32_bf16 v[56:59], v[140:143], v[210:213], v[56:59]
	v_mfma_f32_16x16x32_bf16 v[44:47], v[132:135], v[218:221], v[44:47]
	v_mfma_f32_16x16x32_bf16 v[40:43], v[140:143], v[218:221], v[40:43]
	v_mfma_f32_16x16x32_bf16 v[28:31], v[132:135], v[226:229], v[28:31]
	v_mfma_f32_16x16x32_bf16 v[24:27], v[140:143], v[226:229], v[24:27]
	v_mfma_f32_16x16x32_bf16 v[12:15], v[132:135], v[234:237], v[12:15]
	v_mfma_f32_16x16x32_bf16 v[8:11], v[140:143], v[234:237], v[8:11]
	s_setprio 0
	s_setprio 1
	v_mfma_f32_16x16x32_bf16 v[52:55], v[144:147], v[206:209], v[52:55]
	v_mfma_f32_16x16x32_bf16 v[48:51], v[186:189], v[206:209], v[48:51]
	v_mfma_f32_16x16x32_bf16 v[36:39], v[144:147], v[214:217], v[36:39]
	v_mfma_f32_16x16x32_bf16 v[32:35], v[186:189], v[214:217], v[32:35]
	v_mfma_f32_16x16x32_bf16 v[20:23], v[144:147], v[222:225], v[20:23]
	v_mfma_f32_16x16x32_bf16 v[16:19], v[186:189], v[222:225], v[16:19]
	v_mfma_f32_16x16x32_bf16 v[4:7], v[144:147], v[230:233], v[4:7]
	v_mfma_f32_16x16x32_bf16 v[0:3], v[186:189], v[230:233], v[0:3]
	v_mfma_f32_16x16x32_bf16 v[52:55], v[148:151], v[210:213], v[52:55]
	v_mfma_f32_16x16x32_bf16 v[48:51], v[202:205], v[210:213], v[48:51]
	v_mfma_f32_16x16x32_bf16 v[36:39], v[148:151], v[218:221], v[36:39]
	v_mfma_f32_16x16x32_bf16 v[32:35], v[202:205], v[218:221], v[32:35]
	v_mfma_f32_16x16x32_bf16 v[20:23], v[148:151], v[226:229], v[20:23]
	v_mfma_f32_16x16x32_bf16 v[16:19], v[202:205], v[226:229], v[16:19]
	v_mfma_f32_16x16x32_bf16 v[4:7], v[148:151], v[234:237], v[4:7]
	v_mfma_f32_16x16x32_bf16 v[0:3], v[202:205], v[234:237], v[0:3]
	s_setprio 0
	s_barrier
; #define PG8_STAGE(bufoff, gbase, voff) do { _Pragma("unroll") for (int _i = 0; _i < 2; ++_i) \
;         __builtin_amdgcn_global_load_lds((const unsigned*)((const char*)(gbase) + (voff)[_i]), (LAS unsigned*)(lds + (bufoff) + ldsw + _i * 8192), 16, 0, 0); } while (0)
; #define PG8_LDA(dst, b, h) do { _Pragma("unroll") for (int m = 0; m < 4; ++m) _Pragma("unroll") for (int k = 0; k < 2; ++k) dst[m][k] = *(const LAS bf16x8*)(lds + PG8_SA(b, h) + aoff + m * 2048 + k * 1024); } while (0)
; #define PG8_LDB(dst, b, h) do { _Pragma("unroll") for (int n = 0; n < 2; ++n) _Pragma("unroll") for (int k = 0; k < 2; ++k) dst[n][k] = *(const LAS bf16x8*)(lds + PG8_SB(b, h) + boff + n * 2048 + k * 1024); } while (0)
; #define PG8_MMA(ai, bj, At, Bt) do { __builtin_amdgcn_s_setprio(1); _Pragma("unroll") for (int m = 0; m < 4; ++m) _Pragma("unroll") for (int n = 0; n < 2; ++n) _Pragma("unroll") for (int k = 0; k < 2; ++k) \
;         acc[ai][bj][m][n] = __builtin_amdgcn_mfma_f32_16x16x32_bf16(Bt[n][k], At[m][k], acc[ai][bj][m][n], 0, 0, 0); __builtin_amdgcn_s_setprio(0); } while (0)
; #define PG8_WAIT_V(n) asm volatile("s_waitcnt vmcnt(" #n ")" ::: "memory")
; #define PG8_WAIT_L(n) asm volatile("s_waitcnt lgkmcnt(" #n ")" ::: "memory")
; #define PG8_BAR __builtin_amdgcn_s_barrier()
; #define PG8_SCHED __builtin_amdgcn_sched_barrier(0)
; template <class Epi, class Sched>
; __device__ __forceinline__ void gemm_phase(LAS unsigned char* lds, const Sched& S, const Epi& E, bool natural = false) {
;     ...
;             PG8_LDB(B0, 1, 0); PG8_LDB(B1, 1, 1); PG8_SCHED; PG8_LDA(At, 1, 0); PG8_STAGE(PG8_SA(0, 1), a2 + hstep, voffA);
;             PG8_WAIT_V(8); PG8_WAIT_L(0); PG8_BAR; PG8_MMA(0, 0, At, B0); PG8_MMA(0, 1, At, B1); PG8_BAR; PG8_SCHED;
	s_add_i32 s72, 0, 0x18000
	s_add_i32 s73, 0, 0x1c000
	v_add_u32_e32 v140, s72, v192
	v_add_u32_e32 v166, s73, v192
	ds_read_b128 v[128:131], v140
	ds_read_b128 v[132:135], v140 offset:1024
	ds_read_b128 v[136:139], v140 offset:2048
	ds_read_b128 v[140:143], v140 offset:3072
	ds_read_b128 v[144:147], v166
	ds_read_b128 v[148:151], v166 offset:1024
	ds_read_b128 v[186:189], v166 offset:2048
	ds_read_b128 v[202:205], v166 offset:3072
	s_add_u32 s44, s44, 0x40000
	s_addc_u32 s45, s45, 0
	s_mov_b32 m0, s47
	v_lshl_add_u64 v[246:247], s[44:45], 0, v[154:155]
	ds_read_b128 v[206:209], v198 offset:32768
	ds_read_b128 v[210:213], v198 offset:33792
	ds_read_b128 v[214:217], v198 offset:34816
	ds_read_b128 v[218:221], v198 offset:35840
	ds_read_b128 v[222:225], v198 offset:36864
	ds_read_b128 v[226:229], v198 offset:37888
	ds_read_b128 v[230:233], v198 offset:38912
	ds_read_b128 v[234:237], v198 offset:39936
	global_load_lds_dwordx4 v[246:247], off
	v_lshl_add_u64 v[246:247], s[44:45], 0, v[160:161]
	s_mov_b32 m0, s49
	s_nop 0
	global_load_lds_dwordx4 v[246:247], off
	s_waitcnt vmcnt(8)
	s_waitcnt lgkmcnt(0)
	s_barrier
	s_setprio 1
	s_waitcnt lgkmcnt(0)
	v_mfma_f32_16x16x32_bf16 v[124:127], v[128:131], v[206:209], v[124:127]
	v_mfma_f32_16x16x32_bf16 v[120:123], v[136:139], v[206:209], v[120:123]
	v_mfma_f32_16x16x32_bf16 v[108:111], v[128:131], v[214:217], v[108:111]
	v_mfma_f32_16x16x32_bf16 v[104:107], v[136:139], v[214:217], v[104:107]
	v_mfma_f32_16x16x32_bf16 v[92:95], v[128:131], v[222:225], v[92:95]
	v_mfma_f32_16x16x32_bf16 v[88:91], v[136:139], v[222:225], v[88:91]
	v_mfma_f32_16x16x32_bf16 v[76:79], v[128:131], v[230:233], v[76:79]
	v_mfma_f32_16x16x32_bf16 v[72:75], v[136:139], v[230:233], v[72:75]
	v_mfma_f32_16x16x32_bf16 v[124:127], v[132:135], v[210:213], v[124:127]
	v_mfma_f32_16x16x32_bf16 v[120:123], v[140:143], v[210:213], v[120:123]
	v_mfma_f32_16x16x32_bf16 v[108:111], v[132:135], v[218:221], v[108:111]
	v_mfma_f32_16x16x32_bf16 v[104:107], v[140:143], v[218:221], v[104:107]
	v_mfma_f32_16x16x32_bf16 v[92:95], v[132:135], v[226:229], v[92:95]
	v_mfma_f32_16x16x32_bf16 v[88:91], v[140:143], v[226:229], v[88:91]
	v_mfma_f32_16x16x32_bf16 v[76:79], v[132:135], v[234:237], v[76:79]
	v_mfma_f32_16x16x32_bf16 v[72:75], v[140:143], v[234:237], v[72:75]
	s_setprio 0
	s_setprio 1
	v_mfma_f32_16x16x32_bf16 v[116:119], v[144:147], v[206:209], v[116:119]
	v_mfma_f32_16x16x32_bf16 v[112:115], v[186:189], v[206:209], v[112:115]
	v_mfma_f32_16x16x32_bf16 v[100:103], v[144:147], v[214:217], v[100:103]
	v_mfma_f32_16x16x32_bf16 v[96:99], v[186:189], v[214:217], v[96:99]
	v_mfma_f32_16x16x32_bf16 v[84:87], v[144:147], v[222:225], v[84:87]
	v_mfma_f32_16x16x32_bf16 v[80:83], v[186:189], v[222:225], v[80:83]
	v_mfma_f32_16x16x32_bf16 v[68:71], v[144:147], v[230:233], v[68:71]
	v_mfma_f32_16x16x32_bf16 v[64:67], v[186:189], v[230:233], v[64:67]
	v_mfma_f32_16x16x32_bf16 v[116:119], v[148:151], v[210:213], v[116:119]
	v_mfma_f32_16x16x32_bf16 v[112:115], v[202:205], v[210:213], v[112:115]
	v_mfma_f32_16x16x32_bf16 v[100:103], v[148:151], v[218:221], v[100:103]
	v_mfma_f32_16x16x32_bf16 v[96:99], v[202:205], v[218:221], v[96:99]
	v_mfma_f32_16x16x32_bf16 v[84:87], v[148:151], v[226:229], v[84:87]
	v_mfma_f32_16x16x32_bf16 v[80:83], v[202:205], v[226:229], v[80:83]
	v_mfma_f32_16x16x32_bf16 v[68:71], v[148:151], v[234:237], v[68:71]
	v_mfma_f32_16x16x32_bf16 v[64:67], v[202:205], v[234:237], v[64:67]
	s_setprio 0
	s_barrier
; #define PG8_STAGE(bufoff, gbase, voff) do { _Pragma("unroll") for (int _i = 0; _i < 2; ++_i) \
;         __builtin_amdgcn_global_load_lds((const unsigned*)((const char*)(gbase) + (voff)[_i]), (LAS unsigned*)(lds + (bufoff) + ldsw + _i * 8192), 16, 0, 0); } while (0)
; #define PG8_LDA(dst, b, h) do { _Pragma("unroll") for (int m = 0; m < 4; ++m) _Pragma("unroll") for (int k = 0; k < 2; ++k) dst[m][k] = *(const LAS bf16x8*)(lds + PG8_SA(b, h) + aoff + m * 2048 + k * 1024); } while (0)
; #define PG8_MMA(ai, bj, At, Bt) do { __builtin_amdgcn_s_setprio(1); _Pragma("unroll") for (int m = 0; m < 4; ++m) _Pragma("unroll") for (int n = 0; n < 2; ++n) _Pragma("unroll") for (int k = 0; k < 2; ++k) \
;         acc[ai][bj][m][n] = __builtin_amdgcn_mfma_f32_16x16x32_bf16(Bt[n][k], At[m][k], acc[ai][bj][m][n], 0, 0, 0); __builtin_amdgcn_s_setprio(0); } while (0)
; #define PG8_WAIT_V(n) asm volatile("s_waitcnt vmcnt(" #n ")" ::: "memory")
; #define PG8_WAIT_L(n) asm volatile("s_waitcnt lgkmcnt(" #n ")" ::: "memory")
; #define PG8_BAR __builtin_amdgcn_s_barrier()
; #define PG8_SCHED __builtin_amdgcn_sched_barrier(0)
; template <class Epi, class Sched>
; __device__ __forceinline__ void gemm_phase(LAS unsigned char* lds, const Sched& S, const Epi& E, bool natural = false) {
;     ...
;             PG8_LDA(At, 1, 1); PG8_STAGE(PG8_SB(1, 0), b3, voffB0); PG8_STAGE(PG8_SB(1, 1), b3, voffB1); PG8_STAGE(PG8_SA(1, 0), a3, voffA);
;             PG8_WAIT_V(8); PG8_WAIT_L(0); PG8_BAR; PG8_MMA(1, 0, At, B0); PG8_MMA(1, 1, At, B1); PG8_BAR; PG8_SCHED;
;         }
;         if (wr == 0) PG8_BAR;
	s_add_u32 s42, s42, 0x80
	s_addc_u32 s43, s43, 0
	s_add_i32 s44, s72, s33
	v_lshl_add_u64 v[238:239], v[238:239], 0, s[12:13]
	s_mov_b32 m0, s44
	ds_read_b128 v[206:209], v198 offset:49152
	ds_read_b128 v[210:213], v198 offset:50176
	ds_read_b128 v[214:217], v198 offset:51200
	ds_read_b128 v[218:221], v198 offset:52224
	ds_read_b128 v[222:225], v198 offset:53248
	ds_read_b128 v[226:229], v198 offset:54272
	ds_read_b128 v[230:233], v198 offset:55296
	ds_read_b128 v[234:237], v198 offset:56320
	global_load_lds_dwordx4 v[238:239], off
	v_lshl_add_u64 v[238:239], v[240:241], 0, s[12:13]
	s_add_i32 m0, s44, 0x2000
	s_add_i32 s44, s73, s33
	global_load_lds_dwordx4 v[238:239], off
	v_lshl_add_u64 v[238:239], s[42:43], 0, v[158:159]
	s_mov_b32 m0, s44
	s_nop 0
	global_load_lds_dwordx4 v[238:239], off
	v_lshl_add_u64 v[238:239], s[42:43], 0, v[164:165]
	s_add_i32 m0, s44, 0x2000
	s_nop 0
	global_load_lds_dwordx4 v[238:239], off
	v_lshl_add_u64 v[238:239], v[242:243], 0, s[12:13]
	s_mov_b32 m0, s51
	s_nop 0
	global_load_lds_dwordx4 v[238:239], off
	v_lshl_add_u64 v[238:239], v[244:245], 0, s[12:13]
	s_mov_b32 m0, s52
	s_nop 0
	global_load_lds_dwordx4 v[238:239], off
	s_waitcnt vmcnt(8)
	s_waitcnt lgkmcnt(0)
	s_barrier
	s_setprio 1
	s_waitcnt lgkmcnt(0)
	v_mfma_f32_16x16x32_bf16 v[60:63], v[128:131], v[206:209], v[60:63]
	v_mfma_f32_16x16x32_bf16 v[56:59], v[136:139], v[206:209], v[56:59]
	v_mfma_f32_16x16x32_bf16 v[44:47], v[128:131], v[214:217], v[44:47]
	v_mfma_f32_16x16x32_bf16 v[40:43], v[136:139], v[214:217], v[40:43]
	v_mfma_f32_16x16x32_bf16 v[28:31], v[128:131], v[222:225], v[28:31]
	v_mfma_f32_16x16x32_bf16 v[24:27], v[136:139], v[222:225], v[24:27]
	v_mfma_f32_16x16x32_bf16 v[12:15], v[128:131], v[230:233], v[12:15]
	v_mfma_f32_16x16x32_bf16 v[8:11], v[136:139], v[230:233], v[8:11]
	v_mfma_f32_16x16x32_bf16 v[60:63], v[132:135], v[210:213], v[60:63]
	v_mfma_f32_16x16x32_bf16 v[56:59], v[140:143], v[210:213], v[56:59]
	v_mfma_f32_16x16x32_bf16 v[44:47], v[132:135], v[218:221], v[44:47]
	v_mfma_f32_16x16x32_bf16 v[40:43], v[140:143], v[218:221], v[40:43]
	v_mfma_f32_16x16x32_bf16 v[28:31], v[132:135], v[226:229], v[28:31]
	v_mfma_f32_16x16x32_bf16 v[24:27], v[140:143], v[226:229], v[24:27]
	v_mfma_f32_16x16x32_bf16 v[12:15], v[132:135], v[234:237], v[12:15]
	v_mfma_f32_16x16x32_bf16 v[8:11], v[140:143], v[234:237], v[8:11]
	s_setprio 0
	s_setprio 1
	v_mfma_f32_16x16x32_bf16 v[52:55], v[144:147], v[206:209], v[52:55]
	v_mfma_f32_16x16x32_bf16 v[48:51], v[186:189], v[206:209], v[48:51]
	v_mfma_f32_16x16x32_bf16 v[36:39], v[144:147], v[214:217], v[36:39]
	v_mfma_f32_16x16x32_bf16 v[32:35], v[186:189], v[214:217], v[32:35]
	v_mfma_f32_16x16x32_bf16 v[20:23], v[144:147], v[222:225], v[20:23]
	v_mfma_f32_16x16x32_bf16 v[16:19], v[186:189], v[222:225], v[16:19]
	v_mfma_f32_16x16x32_bf16 v[4:7], v[144:147], v[230:233], v[4:7]
	v_mfma_f32_16x16x32_bf16 v[0:3], v[186:189], v[230:233], v[0:3]
	v_mfma_f32_16x16x32_bf16 v[52:55], v[148:151], v[210:213], v[52:55]
	v_mfma_f32_16x16x32_bf16 v[48:51], v[202:205], v[210:213], v[48:51]
	v_mfma_f32_16x16x32_bf16 v[36:39], v[148:151], v[218:221], v[36:39]
	v_mfma_f32_16x16x32_bf16 v[32:35], v[202:205], v[218:221], v[32:35]
	v_mfma_f32_16x16x32_bf16 v[20:23], v[148:151], v[226:229], v[20:23]
	v_mfma_f32_16x16x32_bf16 v[16:19], v[202:205], v[226:229], v[16:19]
	v_mfma_f32_16x16x32_bf16 v[4:7], v[148:151], v[234:237], v[4:7]
	v_mfma_f32_16x16x32_bf16 v[0:3], v[202:205], v[234:237], v[0:3]
	s_add_i32 s71, s71, 2
	s_add_u32 s40, s40, 0x100
	s_addc_u32 s41, s41, 0
	s_add_u32 s31, s31, 0x100
	s_addc_u32 s35, s35, 0
	s_cmp_gt_u32 s71, 13
	s_setprio 0
	s_barrier
	s_cbranch_scc0 .LBB0_174
	s_and_b64 vcc, exec, s[14:15]
	s_cbranch_vccz .LBB0_179
	s_barrier
	s_branch .LBB0_179
